# ssq loads hoisted in final-layer epilogue; redundant back-to-back setprio pairs removed from the in-projection K-loop
# speedup vs baseline: 1.0084x; 1.0020x over previous
; #define PG8_STAGE(bufoff, gbase, voff) do { _Pragma("unroll") for (int _i = 0; _i < 2; ++_i) \
;         __builtin_amdgcn_global_load_lds((const unsigned*)((const char*)(gbase) + (voff)[_i]), (PG8_LAS unsigned*)(lds + (bufoff) + ldsw + _i * 8192), 16, 0, 0); } while (0)
; #define PG8_LDA(dst, b, h) do { _Pragma("unroll") for (int m = 0; m < 4; ++m) _Pragma("unroll") for (int k = 0; k < 2; ++k) dst[m][k] = *(const PG8_LAS bf16x8*)(lds + PG8_SA(b, h) + aoff + m * 2048 + k * 1024); } while (0)
; #define PG8_LDB(dst, b, h) do { _Pragma("unroll") for (int n = 0; n < 2; ++n) _Pragma("unroll") for (int k = 0; k < 2; ++k) dst[n][k] = *(const PG8_LAS bf16x8*)(lds + PG8_SB(b, h) + boff + n * 2048 + k * 1024); } while (0)
; #define PG8_MMA(ai, bj, At, Bt) do { __builtin_amdgcn_s_setprio(1); _Pragma("unroll") for (int m = 0; m < 4; ++m) _Pragma("unroll") for (int n = 0; n < 2; ++n) _Pragma("unroll") for (int k = 0; k < 2; ++k) \
;         acc[ai][bj][m][n] = __builtin_amdgcn_mfma_f32_16x16x32_bf16(Bt[n][k], At[m][k], acc[ai][bj][m][n], 0, 0, 0); __builtin_amdgcn_s_setprio(0); } while (0)
; #define PG8_WAIT_V(n) asm volatile("s_waitcnt vmcnt(" #n ")" ::: "memory")
; #define PG8_WAIT_L(n) asm volatile("s_waitcnt lgkmcnt(" #n ")" ::: "memory")
; #define PG8_BAR __builtin_amdgcn_s_barrier()
; #define PG8_SCHED __builtin_amdgcn_sched_barrier(0)
; template <class Epi, class Sched, bool ALIGN_EPI = false, bool SP2 = false>
; __device__ __forceinline__ void gemm_phase(PG8_LAS unsigned char* lds, const Gemm g, const Sched& S, const Epi& E) {
;     ...
;             PG8_LDB(B0, 0, 0); PG8_LDB(B1, 0, 1); PG8_SCHED; PG8_LDA(At, 0, 0); PG8_STAGE(PG8_SA(1, 1), a1 + hstep, voffA);
;             PG8_WAIT_V(8); PG8_WAIT_L(0); PG8_BAR; PG8_MMA(0, 0, At, B0); PG8_MMA(0, 1, At, B1); PG8_BAR; PG8_SCHED;
;             PG8_LDA(At, 0, 1); PG8_STAGE(PG8_SB(0, 0), b2, voffB); PG8_STAGE(PG8_SB(0, 1), b2 + hstep, voffB); PG8_STAGE(PG8_SA(0, 0), a2, voffA);
;             PG8_WAIT_V(8); PG8_WAIT_L(0); PG8_BAR; PG8_MMA(1, 0, At, B0); PG8_MMA(1, 1, At, B1); PG8_BAR; PG8_SCHED;
.LBB0_123:
	s_add_u32 s8, s6, 0xfff80080
	s_addc_u32 s9, s7, -1
	s_add_i32 s43, 0, 0x10000
	s_cmp_eq_u32 s42, 28
	s_cselect_b32 s23, s15, s9
	s_cselect_b32 s22, s24, s8
	s_cselect_b32 s9, s17, s41
	s_cselect_b32 s8, s25, s40
	s_add_i32 s48, 0, 0x14000
	v_add_u32_e32 v172, s43, v165
	v_add_u32_e32 v188, s48, v165
	ds_read_b128 v[156:159], v172
	ds_read_b128 v[160:163], v172 offset:1024
	ds_read_b128 v[168:171], v172 offset:2048
	ds_read_b128 v[172:175], v172 offset:3072
	ds_read_b128 v[176:179], v188
	ds_read_b128 v[180:183], v188 offset:1024
	ds_read_b128 v[184:187], v188 offset:2048
	ds_read_b128 v[188:191], v188 offset:3072
	v_lshl_add_u64 v[228:229], s[6:7], 0, v[152:153]
	s_add_i32 m0, s31, 0xc000
	ds_read_b128 v[192:195], v167
	ds_read_b128 v[196:199], v167 offset:1024
	ds_read_b128 v[200:203], v167 offset:2048
	ds_read_b128 v[204:207], v167 offset:3072
	ds_read_b128 v[208:211], v167 offset:4096
	ds_read_b128 v[212:215], v167 offset:5120
	ds_read_b128 v[216:219], v167 offset:6144
	ds_read_b128 v[224:227], v167 offset:7168
	global_load_lds_dwordx4 v[228:229], off
	v_lshl_add_u64 v[228:229], s[6:7], 0, v[154:155]
	s_add_i32 m0, s31, 0xe000
	s_nop 0
	global_load_lds_dwordx4 v[228:229], off
	s_waitcnt vmcnt(8)
	s_waitcnt lgkmcnt(0)
	s_barrier
	s_setprio 1
	s_waitcnt lgkmcnt(0)
	v_mfma_f32_16x16x32_bf16 v[144:147], v[156:159], v[192:195], v[144:147]
	v_mfma_f32_16x16x32_bf16 v[122:125], v[168:171], v[192:195], v[122:125]
	v_mfma_f32_16x16x32_bf16 v[110:113], v[156:159], v[200:203], v[110:113]
	v_mfma_f32_16x16x32_bf16 v[106:109], v[168:171], v[200:203], v[106:109]
	v_mfma_f32_16x16x32_bf16 v[94:97], v[156:159], v[208:211], v[94:97]
	v_mfma_f32_16x16x32_bf16 v[90:93], v[168:171], v[208:211], v[90:93]
	v_mfma_f32_16x16x32_bf16 v[78:81], v[156:159], v[216:219], v[78:81]
	v_mfma_f32_16x16x32_bf16 v[74:77], v[168:171], v[216:219], v[74:77]
	v_mfma_f32_16x16x32_bf16 v[144:147], v[160:163], v[196:199], v[144:147]
	v_mfma_f32_16x16x32_bf16 v[122:125], v[172:175], v[196:199], v[122:125]
	v_mfma_f32_16x16x32_bf16 v[110:113], v[160:163], v[204:207], v[110:113]
	v_mfma_f32_16x16x32_bf16 v[106:109], v[172:175], v[204:207], v[106:109]
	v_mfma_f32_16x16x32_bf16 v[94:97], v[160:163], v[212:215], v[94:97]
	v_mfma_f32_16x16x32_bf16 v[90:93], v[172:175], v[212:215], v[90:93]
	v_mfma_f32_16x16x32_bf16 v[78:81], v[160:163], v[224:227], v[78:81]
	v_mfma_f32_16x16x32_bf16 v[74:77], v[172:175], v[224:227], v[74:77]
	v_mfma_f32_16x16x32_bf16 v[118:121], v[176:179], v[192:195], v[118:121]
	v_mfma_f32_16x16x32_bf16 v[114:117], v[184:187], v[192:195], v[114:117]
	v_mfma_f32_16x16x32_bf16 v[102:105], v[176:179], v[200:203], v[102:105]
	v_mfma_f32_16x16x32_bf16 v[98:101], v[184:187], v[200:203], v[98:101]
	v_mfma_f32_16x16x32_bf16 v[86:89], v[176:179], v[208:211], v[86:89]
	v_mfma_f32_16x16x32_bf16 v[82:85], v[184:187], v[208:211], v[82:85]
	v_mfma_f32_16x16x32_bf16 v[70:73], v[176:179], v[216:219], v[70:73]
	v_mfma_f32_16x16x32_bf16 v[66:69], v[184:187], v[216:219], v[66:69]
	v_mfma_f32_16x16x32_bf16 v[118:121], v[180:183], v[196:199], v[118:121]
	v_mfma_f32_16x16x32_bf16 v[114:117], v[188:191], v[196:199], v[114:117]
	v_mfma_f32_16x16x32_bf16 v[102:105], v[180:183], v[204:207], v[102:105]
	v_mfma_f32_16x16x32_bf16 v[98:101], v[188:191], v[204:207], v[98:101]
	v_mfma_f32_16x16x32_bf16 v[86:89], v[180:183], v[212:215], v[86:89]
	v_mfma_f32_16x16x32_bf16 v[82:85], v[188:191], v[212:215], v[82:85]
	v_mfma_f32_16x16x32_bf16 v[70:73], v[180:183], v[224:227], v[70:73]
	v_mfma_f32_16x16x32_bf16 v[66:69], v[188:191], v[224:227], v[66:69]
	s_setprio 0
	s_barrier
	s_add_i32 s43, s43, s30
	v_lshl_add_u64 v[228:229], s[8:9], 0, v[0:1]
	s_mov_b32 m0, s43
	ds_read_b128 v[192:195], v167 offset:16384
	ds_read_b128 v[196:199], v167 offset:17408
	ds_read_b128 v[200:203], v167 offset:18432
	ds_read_b128 v[204:207], v167 offset:19456
	ds_read_b128 v[208:211], v167 offset:20480
	ds_read_b128 v[212:215], v167 offset:21504
	ds_read_b128 v[216:219], v167 offset:22528
	ds_read_b128 v[224:227], v167 offset:23552
	global_load_lds_dwordx4 v[228:229], off
	s_add_i32 m0, s43, 0x2000
	s_add_u32 s82, s8, 0x80000
	v_lshl_add_u64 v[230:231], s[8:9], 0, v[126:127]
	s_addc_u32 s83, s9, 0
	s_add_i32 s43, s48, s30
	global_load_lds_dwordx4 v[230:231], off
	v_lshl_add_u64 v[232:233], s[82:83], 0, v[0:1]
	s_mov_b32 m0, s43
	v_lshl_add_u64 v[244:245], s[22:23], 0, v[148:149]
	global_load_lds_dwordx4 v[232:233], off
	v_lshl_add_u64 v[232:233], s[82:83], 0, v[126:127]
	s_add_i32 m0, s43, 0x2000
	s_nop 0
	global_load_lds_dwordx4 v[232:233], off
	v_lshl_add_u64 v[232:233], s[22:23], 0, v[150:151]
	s_mov_b32 m0, s31
	s_nop 0
	global_load_lds_dwordx4 v[232:233], off
	s_mov_b32 m0, s34
	s_nop 0
	global_load_lds_dwordx4 v[244:245], off
	s_waitcnt vmcnt(8)
	s_waitcnt lgkmcnt(0)
	s_barrier
; #define PG8_STAGE(bufoff, gbase, voff) do { _Pragma("unroll") for (int _i = 0; _i < 2; ++_i) \
;         __builtin_amdgcn_global_load_lds((const unsigned*)((const char*)(gbase) + (voff)[_i]), (PG8_LAS unsigned*)(lds + (bufoff) + ldsw + _i * 8192), 16, 0, 0); } while (0)
; #define PG8_LDA(dst, b, h) do { _Pragma("unroll") for (int m = 0; m < 4; ++m) _Pragma("unroll") for (int k = 0; k < 2; ++k) dst[m][k] = *(const PG8_LAS bf16x8*)(lds + PG8_SA(b, h) + aoff + m * 2048 + k * 1024); } while (0)
; #define PG8_LDB(dst, b, h) do { _Pragma("unroll") for (int n = 0; n < 2; ++n) _Pragma("unroll") for (int k = 0; k < 2; ++k) dst[n][k] = *(const PG8_LAS bf16x8*)(lds + PG8_SB(b, h) + boff + n * 2048 + k * 1024); } while (0)
; #define PG8_MMA(ai, bj, At, Bt) do { __builtin_amdgcn_s_setprio(1); _Pragma("unroll") for (int m = 0; m < 4; ++m) _Pragma("unroll") for (int n = 0; n < 2; ++n) _Pragma("unroll") for (int k = 0; k < 2; ++k) \
;         acc[ai][bj][m][n] = __builtin_amdgcn_mfma_f32_16x16x32_bf16(Bt[n][k], At[m][k], acc[ai][bj][m][n], 0, 0, 0); __builtin_amdgcn_s_setprio(0); } while (0)
; #define PG8_WAIT_V(n) asm volatile("s_waitcnt vmcnt(" #n ")" ::: "memory")
; #define PG8_WAIT_L(n) asm volatile("s_waitcnt lgkmcnt(" #n ")" ::: "memory")
; #define PG8_BAR __builtin_amdgcn_s_barrier()
; #define PG8_SCHED __builtin_amdgcn_sched_barrier(0)
; template <class Epi, class Sched, bool ALIGN_EPI = false, bool SP2 = false>
; __device__ __forceinline__ void gemm_phase(PG8_LAS unsigned char* lds, const Gemm g, const Sched& S, const Epi& E) {
;     ...
;             PG8_WAIT_V(8); PG8_WAIT_L(0); PG8_BAR; PG8_MMA(0, 0, At, B0); PG8_MMA(0, 1, At, B1); PG8_BAR; PG8_SCHED;
;             PG8_LDA(At, 0, 1); PG8_STAGE(PG8_SB(0, 0), b2, voffB); PG8_STAGE(PG8_SB(0, 1), b2 + hstep, voffB); PG8_STAGE(PG8_SA(0, 0), a2, voffA);
;             PG8_WAIT_V(8); PG8_WAIT_L(0); PG8_BAR; PG8_MMA(1, 0, At, B0); PG8_MMA(1, 1, At, B1); PG8_BAR; PG8_SCHED;
;             PG8_LDB(B0, 1, 0); PG8_LDB(B1, 1, 1); PG8_SCHED; PG8_LDA(At, 1, 0); PG8_STAGE(PG8_SA(0, 1), a2 + hstep, voffA);
;             PG8_WAIT_V(8); PG8_WAIT_L(0); PG8_BAR; PG8_MMA(0, 0, At, B0); PG8_MMA(0, 1, At, B1); PG8_BAR; PG8_SCHED;
	s_setprio 1
	s_waitcnt lgkmcnt(0)
	v_mfma_f32_16x16x32_bf16 v[62:65], v[156:159], v[192:195], v[62:65]
	v_mfma_f32_16x16x32_bf16 v[58:61], v[168:171], v[192:195], v[58:61]
	v_mfma_f32_16x16x32_bf16 v[46:49], v[156:159], v[200:203], v[46:49]
	v_mfma_f32_16x16x32_bf16 v[42:45], v[168:171], v[200:203], v[42:45]
	v_mfma_f32_16x16x32_bf16 v[30:33], v[156:159], v[208:211], v[30:33]
	v_mfma_f32_16x16x32_bf16 v[26:29], v[168:171], v[208:211], v[26:29]
	v_mfma_f32_16x16x32_bf16 v[14:17], v[156:159], v[216:219], v[14:17]
	v_mfma_f32_16x16x32_bf16 v[10:13], v[168:171], v[216:219], v[10:13]
	v_mfma_f32_16x16x32_bf16 v[62:65], v[160:163], v[196:199], v[62:65]
	v_mfma_f32_16x16x32_bf16 v[58:61], v[172:175], v[196:199], v[58:61]
	v_mfma_f32_16x16x32_bf16 v[46:49], v[160:163], v[204:207], v[46:49]
	v_mfma_f32_16x16x32_bf16 v[42:45], v[172:175], v[204:207], v[42:45]
	v_mfma_f32_16x16x32_bf16 v[30:33], v[160:163], v[212:215], v[30:33]
	v_mfma_f32_16x16x32_bf16 v[26:29], v[172:175], v[212:215], v[26:29]
	v_mfma_f32_16x16x32_bf16 v[14:17], v[160:163], v[224:227], v[14:17]
	v_mfma_f32_16x16x32_bf16 v[10:13], v[172:175], v[224:227], v[10:13]
	v_mfma_f32_16x16x32_bf16 v[54:57], v[176:179], v[192:195], v[54:57]
	v_mfma_f32_16x16x32_bf16 v[50:53], v[184:187], v[192:195], v[50:53]
	v_mfma_f32_16x16x32_bf16 v[38:41], v[176:179], v[200:203], v[38:41]
	v_mfma_f32_16x16x32_bf16 v[34:37], v[184:187], v[200:203], v[34:37]
	v_mfma_f32_16x16x32_bf16 v[22:25], v[176:179], v[208:211], v[22:25]
	v_mfma_f32_16x16x32_bf16 v[18:21], v[184:187], v[208:211], v[18:21]
	v_mfma_f32_16x16x32_bf16 v[6:9], v[176:179], v[216:219], v[6:9]
	v_mfma_f32_16x16x32_bf16 v[2:5], v[184:187], v[216:219], v[2:5]
	v_mfma_f32_16x16x32_bf16 v[54:57], v[180:183], v[196:199], v[54:57]
	v_mfma_f32_16x16x32_bf16 v[50:53], v[188:191], v[196:199], v[50:53]
	v_mfma_f32_16x16x32_bf16 v[38:41], v[180:183], v[204:207], v[38:41]
	v_mfma_f32_16x16x32_bf16 v[34:37], v[188:191], v[204:207], v[34:37]
	v_mfma_f32_16x16x32_bf16 v[22:25], v[180:183], v[212:215], v[22:25]
	v_mfma_f32_16x16x32_bf16 v[18:21], v[188:191], v[212:215], v[18:21]
	v_mfma_f32_16x16x32_bf16 v[6:9], v[180:183], v[224:227], v[6:9]
	v_mfma_f32_16x16x32_bf16 v[2:5], v[188:191], v[224:227], v[2:5]
	s_setprio 0
	s_barrier
	s_add_i32 s43, 0, 0x18000
	s_add_i32 s48, 0, 0x1c000
	v_add_u32_e32 v172, s43, v165
	v_add_u32_e32 v188, s48, v165
	ds_read_b128 v[156:159], v172
	ds_read_b128 v[160:163], v172 offset:1024
	ds_read_b128 v[168:171], v172 offset:2048
	ds_read_b128 v[172:175], v172 offset:3072
	ds_read_b128 v[176:179], v188
	ds_read_b128 v[180:183], v188 offset:1024
	ds_read_b128 v[184:187], v188 offset:2048
	ds_read_b128 v[188:191], v188 offset:3072
	s_add_u32 s22, s22, 0x80000
	s_addc_u32 s23, s23, 0
	s_mov_b32 m0, s35
	v_lshl_add_u64 v[246:247], s[22:23], 0, v[150:151]
	ds_read_b128 v[192:195], v167 offset:32768
	ds_read_b128 v[196:199], v167 offset:33792
	ds_read_b128 v[200:203], v167 offset:34816
	ds_read_b128 v[204:207], v167 offset:35840
	ds_read_b128 v[208:211], v167 offset:36864
	ds_read_b128 v[212:215], v167 offset:37888
	ds_read_b128 v[216:219], v167 offset:38912
	ds_read_b128 v[224:227], v167 offset:39936
	global_load_lds_dwordx4 v[246:247], off
	v_lshl_add_u64 v[246:247], s[22:23], 0, v[148:149]
	s_mov_b32 m0, s36
	s_nop 0
	global_load_lds_dwordx4 v[246:247], off
	s_waitcnt vmcnt(8)
	s_waitcnt lgkmcnt(0)
	s_barrier
	s_setprio 1
	s_waitcnt lgkmcnt(0)
	v_mfma_f32_16x16x32_bf16 v[144:147], v[156:159], v[192:195], v[144:147]
	v_mfma_f32_16x16x32_bf16 v[122:125], v[168:171], v[192:195], v[122:125]
	v_mfma_f32_16x16x32_bf16 v[110:113], v[156:159], v[200:203], v[110:113]
	v_mfma_f32_16x16x32_bf16 v[106:109], v[168:171], v[200:203], v[106:109]
	v_mfma_f32_16x16x32_bf16 v[94:97], v[156:159], v[208:211], v[94:97]
	v_mfma_f32_16x16x32_bf16 v[90:93], v[168:171], v[208:211], v[90:93]
	v_mfma_f32_16x16x32_bf16 v[78:81], v[156:159], v[216:219], v[78:81]
	v_mfma_f32_16x16x32_bf16 v[74:77], v[168:171], v[216:219], v[74:77]
	v_mfma_f32_16x16x32_bf16 v[144:147], v[160:163], v[196:199], v[144:147]
	v_mfma_f32_16x16x32_bf16 v[122:125], v[172:175], v[196:199], v[122:125]
	v_mfma_f32_16x16x32_bf16 v[110:113], v[160:163], v[204:207], v[110:113]
	v_mfma_f32_16x16x32_bf16 v[106:109], v[172:175], v[204:207], v[106:109]
	v_mfma_f32_16x16x32_bf16 v[94:97], v[160:163], v[212:215], v[94:97]
	v_mfma_f32_16x16x32_bf16 v[90:93], v[172:175], v[212:215], v[90:93]
	v_mfma_f32_16x16x32_bf16 v[78:81], v[160:163], v[224:227], v[78:81]
	v_mfma_f32_16x16x32_bf16 v[74:77], v[172:175], v[224:227], v[74:77]
	v_mfma_f32_16x16x32_bf16 v[118:121], v[176:179], v[192:195], v[118:121]
	v_mfma_f32_16x16x32_bf16 v[114:117], v[184:187], v[192:195], v[114:117]
	v_mfma_f32_16x16x32_bf16 v[102:105], v[176:179], v[200:203], v[102:105]
	v_mfma_f32_16x16x32_bf16 v[98:101], v[184:187], v[200:203], v[98:101]
	v_mfma_f32_16x16x32_bf16 v[86:89], v[176:179], v[208:211], v[86:89]
	v_mfma_f32_16x16x32_bf16 v[82:85], v[184:187], v[208:211], v[82:85]
	v_mfma_f32_16x16x32_bf16 v[70:73], v[176:179], v[216:219], v[70:73]
	v_mfma_f32_16x16x32_bf16 v[66:69], v[184:187], v[216:219], v[66:69]
	v_mfma_f32_16x16x32_bf16 v[118:121], v[180:183], v[196:199], v[118:121]
	v_mfma_f32_16x16x32_bf16 v[114:117], v[188:191], v[196:199], v[114:117]
	v_mfma_f32_16x16x32_bf16 v[102:105], v[180:183], v[204:207], v[102:105]
	v_mfma_f32_16x16x32_bf16 v[98:101], v[188:191], v[204:207], v[98:101]
	v_mfma_f32_16x16x32_bf16 v[86:89], v[180:183], v[212:215], v[86:89]
	v_mfma_f32_16x16x32_bf16 v[82:85], v[188:191], v[212:215], v[82:85]
	v_mfma_f32_16x16x32_bf16 v[70:73], v[180:183], v[224:227], v[70:73]
	v_mfma_f32_16x16x32_bf16 v[66:69], v[188:191], v[224:227], v[66:69]
	s_setprio 0
	s_barrier
; #define PG8_STAGE(bufoff, gbase, voff) do { _Pragma("unroll") for (int _i = 0; _i < 2; ++_i) \
;         __builtin_amdgcn_global_load_lds((const unsigned*)((const char*)(gbase) + (voff)[_i]), (PG8_LAS unsigned*)(lds + (bufoff) + ldsw + _i * 8192), 16, 0, 0); } while (0)
; #define PG8_LDA(dst, b, h) do { _Pragma("unroll") for (int m = 0; m < 4; ++m) _Pragma("unroll") for (int k = 0; k < 2; ++k) dst[m][k] = *(const PG8_LAS bf16x8*)(lds + PG8_SA(b, h) + aoff + m * 2048 + k * 1024); } while (0)
; #define PG8_LDB(dst, b, h) do { _Pragma("unroll") for (int n = 0; n < 2; ++n) _Pragma("unroll") for (int k = 0; k < 2; ++k) dst[n][k] = *(const PG8_LAS bf16x8*)(lds + PG8_SB(b, h) + boff + n * 2048 + k * 1024); } while (0)
; #define PG8_MMA(ai, bj, At, Bt) do { __builtin_amdgcn_s_setprio(1); _Pragma("unroll") for (int m = 0; m < 4; ++m) _Pragma("unroll") for (int n = 0; n < 2; ++n) _Pragma("unroll") for (int k = 0; k < 2; ++k) \
;         acc[ai][bj][m][n] = __builtin_amdgcn_mfma_f32_16x16x32_bf16(Bt[n][k], At[m][k], acc[ai][bj][m][n], 0, 0, 0); __builtin_amdgcn_s_setprio(0); } while (0)
; template <class Epi, class Sched, bool ALIGN_EPI = false, bool SP2 = false>
; __device__ __forceinline__ void gemm_phase(PG8_LAS unsigned char* lds, const Gemm g, const Sched& S, const Epi& E) {
;     ...
;         for (int t = 0; t < nt; t += 2) {
;             if constexpr (Epi::HAS_MID) { if (t == Epi::MID0 || t == Epi::MID1) E.mid(acc, cur, wr, wc, fr, fq, t == Epi::MID0 ? 0 : 1); }
;             const bool last = (t == nt - 2);
;             const char* a1 = cA + (size_t)(t + 1) * kstep;
;             const char* a2 = last ? nA : cA + (size_t)(t + 2) * kstep; const char* b2 = last ? nB : cB + (size_t)(t + 2) * kstep;
;             const char* a3 = a2 + kstep; const char* b3 = b2 + kstep;
;             if (last && has_next) S.a_ready(nxt);
;     ...
;             PG8_LDB(B0, 1, 0); PG8_LDB(B1, 1, 1); PG8_SCHED; PG8_LDA(At, 1, 0); PG8_STAGE(PG8_SA(0, 1), a2 + hstep, voffA);
;             PG8_WAIT_V(8); PG8_WAIT_L(0); PG8_BAR; PG8_MMA(0, 0, At, B0); PG8_MMA(0, 1, At, B1); PG8_BAR; PG8_SCHED;
;             PG8_LDA(At, 1, 1); PG8_STAGE(PG8_SB(1, 0), b3, voffB); PG8_STAGE(PG8_SB(1, 1), b3 + hstep, voffB); PG8_STAGE(PG8_SA(1, 0), a3, voffA);
;             PG8_WAIT_V(8); PG8_WAIT_L(0); PG8_BAR; PG8_MMA(1, 0, At, B0); PG8_MMA(1, 1, At, B1); PG8_BAR; PG8_SCHED;
	s_add_i32 s22, s43, s30
	v_lshl_add_u64 v[228:229], v[228:229], 0, s[64:65]
	s_mov_b32 m0, s22
	ds_read_b128 v[192:195], v167 offset:49152
	ds_read_b128 v[196:199], v167 offset:50176
	ds_read_b128 v[200:203], v167 offset:51200
	ds_read_b128 v[204:207], v167 offset:52224
	ds_read_b128 v[208:211], v167 offset:53248
	ds_read_b128 v[212:215], v167 offset:54272
	ds_read_b128 v[216:219], v167 offset:55296
	ds_read_b128 v[224:227], v167 offset:56320
	global_load_lds_dwordx4 v[228:229], off
	s_add_i32 m0, s22, 0x2000
	s_add_u32 s8, s8, 0x80080
	v_lshl_add_u64 v[228:229], v[230:231], 0, s[64:65]
	s_addc_u32 s9, s9, 0
	s_add_i32 s22, s48, s30
	global_load_lds_dwordx4 v[228:229], off
	v_lshl_add_u64 v[228:229], s[8:9], 0, v[0:1]
	s_mov_b32 m0, s22
	s_nop 0
	global_load_lds_dwordx4 v[228:229], off
	v_lshl_add_u64 v[228:229], s[8:9], 0, v[126:127]
	s_add_i32 m0, s22, 0x2000
	s_nop 0
	global_load_lds_dwordx4 v[228:229], off
	v_lshl_add_u64 v[228:229], v[232:233], 0, s[64:65]
	s_mov_b32 m0, s37
	s_nop 0
	global_load_lds_dwordx4 v[228:229], off
	v_lshl_add_u64 v[228:229], v[244:245], 0, s[64:65]
	s_mov_b32 m0, s76
	s_nop 0
	global_load_lds_dwordx4 v[228:229], off
	s_waitcnt vmcnt(8)
	s_waitcnt lgkmcnt(0)
	s_barrier
	s_setprio 1
	s_waitcnt lgkmcnt(0)
	v_mfma_f32_16x16x32_bf16 v[62:65], v[156:159], v[192:195], v[62:65]
	v_mfma_f32_16x16x32_bf16 v[58:61], v[168:171], v[192:195], v[58:61]
	v_mfma_f32_16x16x32_bf16 v[46:49], v[156:159], v[200:203], v[46:49]
	v_mfma_f32_16x16x32_bf16 v[42:45], v[168:171], v[200:203], v[42:45]
	v_mfma_f32_16x16x32_bf16 v[30:33], v[156:159], v[208:211], v[30:33]
	v_mfma_f32_16x16x32_bf16 v[26:29], v[168:171], v[208:211], v[26:29]
	v_mfma_f32_16x16x32_bf16 v[14:17], v[156:159], v[216:219], v[14:17]
	v_mfma_f32_16x16x32_bf16 v[10:13], v[168:171], v[216:219], v[10:13]
	v_mfma_f32_16x16x32_bf16 v[62:65], v[160:163], v[196:199], v[62:65]
	v_mfma_f32_16x16x32_bf16 v[58:61], v[172:175], v[196:199], v[58:61]
	v_mfma_f32_16x16x32_bf16 v[46:49], v[160:163], v[204:207], v[46:49]
	v_mfma_f32_16x16x32_bf16 v[42:45], v[172:175], v[204:207], v[42:45]
	v_mfma_f32_16x16x32_bf16 v[30:33], v[160:163], v[212:215], v[30:33]
	v_mfma_f32_16x16x32_bf16 v[26:29], v[172:175], v[212:215], v[26:29]
	v_mfma_f32_16x16x32_bf16 v[14:17], v[160:163], v[224:227], v[14:17]
	v_mfma_f32_16x16x32_bf16 v[10:13], v[172:175], v[224:227], v[10:13]
	v_mfma_f32_16x16x32_bf16 v[54:57], v[176:179], v[192:195], v[54:57]
	v_mfma_f32_16x16x32_bf16 v[50:53], v[184:187], v[192:195], v[50:53]
	v_mfma_f32_16x16x32_bf16 v[38:41], v[176:179], v[200:203], v[38:41]
	v_mfma_f32_16x16x32_bf16 v[34:37], v[184:187], v[200:203], v[34:37]
	v_mfma_f32_16x16x32_bf16 v[22:25], v[176:179], v[208:211], v[22:25]
	v_mfma_f32_16x16x32_bf16 v[18:21], v[184:187], v[208:211], v[18:21]
	v_mfma_f32_16x16x32_bf16 v[6:9], v[176:179], v[216:219], v[6:9]
	v_mfma_f32_16x16x32_bf16 v[2:5], v[184:187], v[216:219], v[2:5]
	v_mfma_f32_16x16x32_bf16 v[54:57], v[180:183], v[196:199], v[54:57]
	v_mfma_f32_16x16x32_bf16 v[50:53], v[188:191], v[196:199], v[50:53]
	v_mfma_f32_16x16x32_bf16 v[38:41], v[180:183], v[204:207], v[38:41]
	v_mfma_f32_16x16x32_bf16 v[34:37], v[188:191], v[204:207], v[34:37]
	v_mfma_f32_16x16x32_bf16 v[22:25], v[180:183], v[212:215], v[22:25]
	v_mfma_f32_16x16x32_bf16 v[18:21], v[188:191], v[212:215], v[18:21]
	v_mfma_f32_16x16x32_bf16 v[6:9], v[180:183], v[224:227], v[6:9]
	v_mfma_f32_16x16x32_bf16 v[2:5], v[188:191], v[224:227], v[2:5]
	s_setprio 0
	s_barrier
	s_add_i32 s42, s42, 2
	s_add_u32 s6, s6, 0x100
	s_addc_u32 s7, s7, 0
	s_add_u32 s40, s40, 0x100
	s_addc_u32 s41, s41, 0
	s_cmp_gt_u32 s42, 29
	s_cbranch_scc0 .LBB0_123
	s_and_b64 vcc, exec, s[12:13]
	s_cbranch_vccz .LBB0_126
	s_barrier

; __device__ __forceinline__ unsigned cvt_pk_bf16(float lo, float hi) { const f32x2e_t v = {lo, hi}; return __builtin_bit_cast(unsigned, __builtin_convertvector(v, bf16x2e_t)); }
;     __device__ __forceinline__ void operator()(f32x4 (&acc)[2][2][4][2], const Unit& u, int wr, int wc, int fr, int fq) const {
;     ...
;         asm volatile("s_waitcnt vmcnt(0) lgkmcnt(0)" ::: "memory");
;         __builtin_amdgcn_s_barrier();
;         asm volatile("" ::: "memory");
;         f32x4 gv[2][2];
;         if (FINAL) {
; #pragma unroll
;             for (int bj = 0; bj < 2; ++bj)
; #pragma unroll
;                 for (int n = 0; n < 2; ++n) gv[bj][n] = *(const f32x4*)(fgain + col0 + bj * HALF + n * 16); }
; #pragma unroll
;         for (int ai = 0; ai < 2; ++ai)
; #pragma unroll
;             for (int m = 0; m < 4; ++m) { const int row = row0 + ai * HALF + m * 16; const size_t off = (size_t)row * 2048 + col0;
;                 const float r = rsqrtf(__hip_atomic_load(ssq + row, __ATOMIC_RELAXED, __HIP_MEMORY_SCOPE_AGENT) * (1.0f / 2048.0f) + 1e-6f);
; #pragma unroll
;                 for (int bj = 0; bj < 2; ++bj)
; #pragma unroll
;                     for (int n = 0; n < 2; ++n) { const f32x4 xo = acc[ai][bj][m][n] * r;
;                         if (FINAL) *(f32x4*)(X + off + bj * HALF + n * 16) = xo * gv[bj][n];
;                         else { unsigned long long w = (unsigned long long)cvt_pk_bf16(xo[0], xo[1]) | ((unsigned long long)cvt_pk_bf16(xo[2], xo[3]) << 32); *(unsigned long long*)(XB + off + bj * HALF + n * 16) = w; } } }
.LBB0_997:
	s_or_b64 exec, exec, s[0:1]
	s_waitcnt vmcnt(0) lgkmcnt(0)
	s_barrier
	s_waitcnt lgkmcnt(0)
	v_lshl_add_u64 v[2:3], v[154:155], 2, s[56:57]
	global_load_dwordx4 v[14:17], v[2:3], off
	global_load_dwordx4 v[10:13], v[2:3], off offset:64
	global_load_dwordx4 v[6:9], v[2:3], off offset:512
	s_nop 0
	global_load_dwordx4 v[2:5], v[2:3], off offset:576
	s_nop 0
	global_load_dword v204, v[114:115], off sc1
	global_load_dword v205, v[164:165], off sc1
	global_load_dword v206, v[168:169], off sc1
	global_load_dword v207, v[172:173], off sc1
	global_load_dword v208, v[114:115], off offset:512 sc1
	global_load_dword v209, v[114:115], off offset:576 sc1
	global_load_dword v210, v[114:115], off offset:640 sc1
	global_load_dword v211, v[114:115], off offset:704 sc1
	s_waitcnt vmcnt(0)
	v_fmamk_f32 v154, v204, 0x3a000000, v239
	v_mul_f32_e32 v155, 0x4b800000, v154
	v_cmp_gt_f32_e32 vcc, s74, v154
	s_nop 1
	v_cndmask_b32_e32 v154, v154, v155, vcc
	v_rsq_f32_e32 v154, v154
	s_nop 0
	v_mul_f32_e32 v155, 0x45800000, v154
	v_cndmask_b32_e32 v154, v154, v155, vcc
	v_pk_mul_f32 v[144:145], v[144:145], v[154:155] op_sel_hi:[1,0]
	v_pk_mul_f32 v[146:147], v[146:147], v[154:155] op_sel_hi:[1,0]
	v_pk_mul_f32 v[194:195], v[122:123], v[154:155] op_sel_hi:[1,0]
	v_pk_mul_f32 v[122:123], v[124:125], v[154:155] op_sel_hi:[1,0]
	v_pk_mul_f32 v[124:125], v[118:119], v[154:155] op_sel_hi:[1,0]
	v_pk_mul_f32 v[200:201], v[120:121], v[154:155] op_sel_hi:[1,0]
	v_pk_mul_f32 v[202:203], v[156:157], v[154:155] op_sel_hi:[1,0]
	v_pk_mul_f32 v[154:155], v[116:117], v[154:155] op_sel_hi:[1,0]
	v_pk_mul_f32 v[118:119], v[16:17], v[146:147]
	v_pk_mul_f32 v[116:117], v[14:15], v[144:145]
	v_pk_mul_f32 v[122:123], v[12:13], v[122:123]
	v_pk_mul_f32 v[120:121], v[10:11], v[194:195]
	v_pk_mul_f32 v[146:147], v[8:9], v[200:201]
	v_pk_mul_f32 v[144:145], v[6:7], v[124:125]
	v_pk_mul_f32 v[156:157], v[4:5], v[154:155]
	v_pk_mul_f32 v[154:155], v[2:3], v[202:203]
	global_store_dwordx4 v[152:153], v[116:119], off
	global_store_dwordx4 v[152:153], v[120:123], off offset:64
	global_store_dwordx4 v[152:153], v[144:147], off offset:512
	global_store_dwordx4 v[152:153], v[154:157], off offset:576
	v_fmamk_f32 v116, v205, 0x3a000000, v239
	v_mul_f32_e32 v117, 0x4b800000, v116
	v_cmp_gt_f32_e32 vcc, s74, v116
	s_nop 1
	v_cndmask_b32_e32 v116, v116, v117, vcc
	v_rsq_f32_e32 v116, v116
	s_nop 0
	v_mul_f32_e32 v117, 0x45800000, v116
	v_cndmask_b32_e32 v116, v116, v117, vcc
	v_pk_mul_f32 v[110:111], v[110:111], v[116:117] op_sel_hi:[1,0]
	v_pk_mul_f32 v[112:113], v[112:113], v[116:117] op_sel_hi:[1,0]
	v_pk_mul_f32 v[106:107], v[106:107], v[116:117] op_sel_hi:[1,0]
	v_pk_mul_f32 v[108:109], v[108:109], v[116:117] op_sel_hi:[1,0]
	v_pk_mul_f32 v[118:119], v[102:103], v[116:117] op_sel_hi:[1,0]
	v_pk_mul_f32 v[120:121], v[104:105], v[116:117] op_sel_hi:[1,0]
	v_pk_mul_f32 v[122:123], v[98:99], v[116:117] op_sel_hi:[1,0]
	v_pk_mul_f32 v[116:117], v[100:101], v[116:117] op_sel_hi:[1,0]
	v_pk_mul_f32 v[100:101], v[16:17], v[112:113]
	v_pk_mul_f32 v[98:99], v[14:15], v[110:111]
	v_pk_mul_f32 v[104:105], v[12:13], v[108:109]
	v_pk_mul_f32 v[102:103], v[10:11], v[106:107]
	v_pk_mul_f32 v[108:109], v[8:9], v[120:121]
	v_pk_mul_f32 v[106:107], v[6:7], v[118:119]
	v_pk_mul_f32 v[112:113], v[4:5], v[116:117]
	v_pk_mul_f32 v[110:111], v[2:3], v[122:123]
	global_store_dwordx4 v[158:159], v[98:101], off
	global_store_dwordx4 v[158:159], v[102:105], off offset:64
	global_store_dwordx4 v[158:159], v[106:109], off offset:512
	global_store_dwordx4 v[158:159], v[110:113], off offset:576
	v_fmamk_f32 v98, v206, 0x3a000000, v239
	v_mul_f32_e32 v99, 0x4b800000, v98
	v_cmp_gt_f32_e32 vcc, s74, v98
	s_nop 1
	v_cndmask_b32_e32 v98, v98, v99, vcc
	v_rsq_f32_e32 v98, v98
	s_nop 0
	v_mul_f32_e32 v99, 0x45800000, v98
	v_cndmask_b32_e32 v98, v98, v99, vcc
	v_pk_mul_f32 v[94:95], v[94:95], v[98:99] op_sel_hi:[1,0]
	v_pk_mul_f32 v[96:97], v[96:97], v[98:99] op_sel_hi:[1,0]
	v_pk_mul_f32 v[90:91], v[90:91], v[98:99] op_sel_hi:[1,0]
	v_pk_mul_f32 v[92:93], v[92:93], v[98:99] op_sel_hi:[1,0]
	v_pk_mul_f32 v[100:101], v[86:87], v[98:99] op_sel_hi:[1,0]
	v_pk_mul_f32 v[102:103], v[88:89], v[98:99] op_sel_hi:[1,0]
	v_pk_mul_f32 v[104:105], v[82:83], v[98:99] op_sel_hi:[1,0]
	v_pk_mul_f32 v[98:99], v[84:85], v[98:99] op_sel_hi:[1,0]
	v_pk_mul_f32 v[84:85], v[16:17], v[96:97]
	v_pk_mul_f32 v[82:83], v[14:15], v[94:95]
	v_pk_mul_f32 v[88:89], v[12:13], v[92:93]
	v_pk_mul_f32 v[86:87], v[10:11], v[90:91]
	v_pk_mul_f32 v[92:93], v[8:9], v[102:103]
	v_pk_mul_f32 v[90:91], v[6:7], v[100:101]
	v_pk_mul_f32 v[96:97], v[4:5], v[98:99]
	v_pk_mul_f32 v[94:95], v[2:3], v[104:105]
	global_store_dwordx4 v[160:161], v[82:85], off
	global_store_dwordx4 v[160:161], v[86:89], off offset:64
	global_store_dwordx4 v[160:161], v[90:93], off offset:512
	global_store_dwordx4 v[160:161], v[94:97], off offset:576
	v_fmamk_f32 v82, v207, 0x3a000000, v239
	v_mul_f32_e32 v83, 0x4b800000, v82
	v_cmp_gt_f32_e32 vcc, s74, v82
	s_nop 1
	v_cndmask_b32_e32 v82, v82, v83, vcc
	v_rsq_f32_e32 v82, v82
	s_nop 0
	v_mul_f32_e32 v83, 0x45800000, v82
	v_cndmask_b32_e32 v82, v82, v83, vcc
	v_pk_mul_f32 v[78:79], v[78:79], v[82:83] op_sel_hi:[1,0]
	v_pk_mul_f32 v[80:81], v[80:81], v[82:83] op_sel_hi:[1,0]
	v_pk_mul_f32 v[74:75], v[74:75], v[82:83] op_sel_hi:[1,0]
	v_pk_mul_f32 v[76:77], v[76:77], v[82:83] op_sel_hi:[1,0]
	v_pk_mul_f32 v[84:85], v[70:71], v[82:83] op_sel_hi:[1,0]
	v_pk_mul_f32 v[86:87], v[72:73], v[82:83] op_sel_hi:[1,0]
	v_pk_mul_f32 v[88:89], v[66:67], v[82:83] op_sel_hi:[1,0]
	v_pk_mul_f32 v[82:83], v[68:69], v[82:83] op_sel_hi:[1,0]
; __device__ __forceinline__ unsigned cvt_pk_bf16(float lo, float hi) { const f32x2e_t v = {lo, hi}; return __builtin_bit_cast(unsigned, __builtin_convertvector(v, bf16x2e_t)); }
;     __device__ __forceinline__ void operator()(f32x4 (&acc)[2][2][4][2], const Unit& u, int wr, int wc, int fr, int fq) const {
;     ...
;         for (int ai = 0; ai < 2; ++ai)
; #pragma unroll
;             for (int m = 0; m < 4; ++m) { const int row = row0 + ai * HALF + m * 16; const size_t off = (size_t)row * 2048 + col0;
;                 const float r = rsqrtf(__hip_atomic_load(ssq + row, __ATOMIC_RELAXED, __HIP_MEMORY_SCOPE_AGENT) * (1.0f / 2048.0f) + 1e-6f);
; #pragma unroll
;                 for (int bj = 0; bj < 2; ++bj)
; #pragma unroll
;                     for (int n = 0; n < 2; ++n) { const f32x4 xo = acc[ai][bj][m][n] * r;
;                         if (FINAL) *(f32x4*)(X + off + bj * HALF + n * 16) = xo * gv[bj][n];
;                         else { unsigned long long w = (unsigned long long)cvt_pk_bf16(xo[0], xo[1]) | ((unsigned long long)cvt_pk_bf16(xo[2], xo[3]) << 32); *(unsigned long long*)(XB + off + bj * HALF + n * 16) = w; } } }
	v_pk_mul_f32 v[68:69], v[16:17], v[80:81]
	v_pk_mul_f32 v[66:67], v[14:15], v[78:79]
	v_pk_mul_f32 v[72:73], v[12:13], v[76:77]
	v_pk_mul_f32 v[70:71], v[10:11], v[74:75]
	v_pk_mul_f32 v[76:77], v[8:9], v[86:87]
	v_pk_mul_f32 v[74:75], v[6:7], v[84:85]
	v_pk_mul_f32 v[80:81], v[4:5], v[82:83]
	v_pk_mul_f32 v[78:79], v[2:3], v[88:89]
	global_store_dwordx4 v[166:167], v[66:69], off
	global_store_dwordx4 v[166:167], v[70:73], off offset:64
	global_store_dwordx4 v[166:167], v[74:77], off offset:512
	global_store_dwordx4 v[166:167], v[78:81], off offset:576
	v_fmamk_f32 v66, v208, 0x3a000000, v239
	v_mul_f32_e32 v67, 0x4b800000, v66
	v_cmp_gt_f32_e32 vcc, s74, v66
	s_nop 1
	v_cndmask_b32_e32 v66, v66, v67, vcc
	v_rsq_f32_e32 v66, v66
	s_nop 0
	v_mul_f32_e32 v67, 0x45800000, v66
	v_cndmask_b32_e32 v66, v66, v67, vcc
	v_pk_mul_f32 v[62:63], v[62:63], v[66:67] op_sel_hi:[1,0]
	v_pk_mul_f32 v[64:65], v[64:65], v[66:67] op_sel_hi:[1,0]
	v_pk_mul_f32 v[58:59], v[58:59], v[66:67] op_sel_hi:[1,0]
	v_pk_mul_f32 v[60:61], v[60:61], v[66:67] op_sel_hi:[1,0]
	v_pk_mul_f32 v[68:69], v[54:55], v[66:67] op_sel_hi:[1,0]
	v_pk_mul_f32 v[70:71], v[56:57], v[66:67] op_sel_hi:[1,0]
	v_pk_mul_f32 v[72:73], v[50:51], v[66:67] op_sel_hi:[1,0]
	v_pk_mul_f32 v[66:67], v[52:53], v[66:67] op_sel_hi:[1,0]
	v_pk_mul_f32 v[52:53], v[16:17], v[64:65]
	v_pk_mul_f32 v[50:51], v[14:15], v[62:63]
	v_pk_mul_f32 v[56:57], v[12:13], v[60:61]
	v_pk_mul_f32 v[54:55], v[10:11], v[58:59]
	v_pk_mul_f32 v[60:61], v[8:9], v[70:71]
	v_pk_mul_f32 v[58:59], v[6:7], v[68:69]
	v_pk_mul_f32 v[64:65], v[4:5], v[66:67]
	v_pk_mul_f32 v[62:63], v[2:3], v[72:73]
	global_store_dwordx4 v[170:171], v[50:53], off
	global_store_dwordx4 v[170:171], v[54:57], off offset:64
	global_store_dwordx4 v[170:171], v[58:61], off offset:512
	global_store_dwordx4 v[170:171], v[62:65], off offset:576
	v_fmamk_f32 v50, v209, 0x3a000000, v239
	v_mul_f32_e32 v51, 0x4b800000, v50
	v_cmp_gt_f32_e32 vcc, s74, v50
	s_nop 1
	v_cndmask_b32_e32 v50, v50, v51, vcc
	v_rsq_f32_e32 v50, v50
	s_nop 0
	v_mul_f32_e32 v51, 0x45800000, v50
	v_cndmask_b32_e32 v50, v50, v51, vcc
	v_pk_mul_f32 v[46:47], v[46:47], v[50:51] op_sel_hi:[1,0]
	v_pk_mul_f32 v[48:49], v[48:49], v[50:51] op_sel_hi:[1,0]
	v_pk_mul_f32 v[42:43], v[42:43], v[50:51] op_sel_hi:[1,0]
	v_pk_mul_f32 v[44:45], v[44:45], v[50:51] op_sel_hi:[1,0]
	v_pk_mul_f32 v[52:53], v[38:39], v[50:51] op_sel_hi:[1,0]
	v_pk_mul_f32 v[54:55], v[40:41], v[50:51] op_sel_hi:[1,0]
	v_pk_mul_f32 v[56:57], v[34:35], v[50:51] op_sel_hi:[1,0]
	v_pk_mul_f32 v[50:51], v[36:37], v[50:51] op_sel_hi:[1,0]
	v_pk_mul_f32 v[36:37], v[16:17], v[48:49]
	v_pk_mul_f32 v[34:35], v[14:15], v[46:47]
	v_pk_mul_f32 v[40:41], v[12:13], v[44:45]
	v_pk_mul_f32 v[38:39], v[10:11], v[42:43]
	v_pk_mul_f32 v[44:45], v[8:9], v[54:55]
	v_pk_mul_f32 v[42:43], v[6:7], v[52:53]
	v_pk_mul_f32 v[48:49], v[4:5], v[50:51]
	v_pk_mul_f32 v[46:47], v[2:3], v[56:57]
	global_store_dwordx4 v[174:175], v[34:37], off
	global_store_dwordx4 v[174:175], v[38:41], off offset:64
	global_store_dwordx4 v[174:175], v[42:45], off offset:512
	global_store_dwordx4 v[174:175], v[46:49], off offset:576
	v_fmamk_f32 v34, v210, 0x3a000000, v239
	v_mul_f32_e32 v35, 0x4b800000, v34
	v_cmp_gt_f32_e32 vcc, s74, v34
	s_nop 1
	v_cndmask_b32_e32 v34, v34, v35, vcc
	v_rsq_f32_e32 v34, v34
	s_nop 0
	v_mul_f32_e32 v35, 0x45800000, v34
	v_cndmask_b32_e32 v34, v34, v35, vcc
	v_pk_mul_f32 v[30:31], v[30:31], v[34:35] op_sel_hi:[1,0]
	v_pk_mul_f32 v[32:33], v[32:33], v[34:35] op_sel_hi:[1,0]
	v_pk_mul_f32 v[26:27], v[26:27], v[34:35] op_sel_hi:[1,0]
	v_pk_mul_f32 v[28:29], v[28:29], v[34:35] op_sel_hi:[1,0]
	v_pk_mul_f32 v[36:37], v[22:23], v[34:35] op_sel_hi:[1,0]
	v_pk_mul_f32 v[38:39], v[24:25], v[34:35] op_sel_hi:[1,0]
	v_pk_mul_f32 v[40:41], v[18:19], v[34:35] op_sel_hi:[1,0]
	v_pk_mul_f32 v[34:35], v[20:21], v[34:35] op_sel_hi:[1,0]
	v_pk_mul_f32 v[20:21], v[16:17], v[32:33]
	v_pk_mul_f32 v[18:19], v[14:15], v[30:31]
	v_pk_mul_f32 v[24:25], v[12:13], v[28:29]
	v_pk_mul_f32 v[22:23], v[10:11], v[26:27]
	v_pk_mul_f32 v[28:29], v[8:9], v[38:39]
	v_pk_mul_f32 v[26:27], v[6:7], v[36:37]
	v_pk_mul_f32 v[32:33], v[4:5], v[34:35]
	v_pk_mul_f32 v[30:31], v[2:3], v[40:41]
	global_store_dwordx4 v[176:177], v[18:21], off
	global_store_dwordx4 v[176:177], v[22:25], off offset:64
	global_store_dwordx4 v[176:177], v[26:29], off offset:512
	global_store_dwordx4 v[176:177], v[30:33], off offset:576
	s_andn2_b64 vcc, exec, s[6:7]
	v_fmamk_f32 v18, v211, 0x3a000000, v239
	v_mul_f32_e32 v19, 0x4b800000, v18
	v_cmp_gt_f32_e64 s[0:1], s74, v18
	s_nop 1
	v_cndmask_b32_e64 v18, v18, v19, s[0:1]
	v_rsq_f32_e32 v18, v18
	s_nop 0
	v_mul_f32_e32 v19, 0x45800000, v18
	v_cndmask_b32_e64 v18, v18, v19, s[0:1]
	v_pk_mul_f32 v[20:21], v[180:181], v[18:19] op_sel_hi:[1,0]
	v_pk_mul_f32 v[22:23], v[178:179], v[18:19] op_sel_hi:[1,0]
	v_pk_mul_f32 v[24:25], v[184:185], v[18:19] op_sel_hi:[1,0]
	v_pk_mul_f32 v[26:27], v[182:183], v[18:19] op_sel_hi:[1,0]
	v_pk_mul_f32 v[28:29], v[188:189], v[18:19] op_sel_hi:[1,0]
	v_pk_mul_f32 v[30:31], v[186:187], v[18:19] op_sel_hi:[1,0]
	v_pk_mul_f32 v[32:33], v[192:193], v[18:19] op_sel_hi:[1,0]
	v_pk_mul_f32 v[18:19], v[190:191], v[18:19] op_sel_hi:[1,0]
	v_pk_mul_f32 v[16:17], v[16:17], v[22:23]
	v_pk_mul_f32 v[14:15], v[14:15], v[20:21]
	s_mov_b64 s[0:1], -1
	v_pk_mul_f32 v[12:13], v[12:13], v[26:27]
	v_pk_mul_f32 v[10:11], v[10:11], v[24:25]
	v_pk_mul_f32 v[8:9], v[8:9], v[30:31]
	v_pk_mul_f32 v[6:7], v[6:7], v[28:29]
	v_pk_mul_f32 v[4:5], v[4:5], v[18:19]
	v_pk_mul_f32 v[2:3], v[2:3], v[32:33]
	global_store_dwordx4 v[162:163], v[14:17], off
	global_store_dwordx4 v[162:163], v[10:13], off offset:64
	global_store_dwordx4 v[162:163], v[6:9], off offset:512
	global_store_dwordx4 v[162:163], v[2:5], off offset:576
	s_cbranch_vccnz .LBB0_955
	s_andn2_b64 vcc, exec, s[8:9]
	s_cbranch_vccnz .LBB0_954
	s_barrier
	s_branch .LBB0_954
